# matrix-core substitution: two alternating accumulators per row block (no dependent-chain stalls), all right-hand-side reads in flight together
# speedup vs baseline: 1.0124x; 1.0028x over previous
; #define LAS __attribute__((address_space(3)))
; __device__ __forceinline__ float bf2f(unsigned short v) { return __uint_as_float(((unsigned)v) << 16); }
; __device__ __forceinline__ void dn_prep_item(const Args& a, LAS unsigned char* lds, int item, int tid, int wave, int lane, int& cwh, int next_item) {
;     ...
;     if (wave < 4) {
;         float x[64];
;         { const LAS unsigned char* src = lds + (tid < 128 ? L_V : L_KH) + 2 * (tid & 127); const LAS float* fac = tid < 128 ? betas : bks;
; #pragma unroll
;           for (int i = 0; i < 64; ++i) x[i] = bf2f(*(const LAS unsigned short*)(src + i * KS_)) * fac[i]; }
.LBB0_878:
	s_and_b64 vcc, exec, s[22:23]
	s_cbranch_vccz .LBB0_880
	v_and_b32_e32 v234, 3, v206
	v_mul_u32_u24_e32 v234, 0x110, v234
	v_add_u32_e32 v234, 0x8800, v234
	ds_read_b128 v[88:91], v190
	ds_read_b128 v[92:95], v191
	ds_read_b128 v[96:99], v192
	ds_read_b128 v[100:103], v193
	ds_read_b128 v[104:107], v194
	ds_read_b128 v[108:111], v195
	ds_read_b128 v[112:115], v196
	ds_read_b128 v[116:119], v197
	ds_read_b128 v[120:123], v198
	ds_read_b128 v[124:127], v199
	ds_read_b128 v[128:131], v201
	ds_read_b128 v[132:135], v202
	ds_read_b128 v[136:139], v203
	ds_read_b128 v[140:143], v204
	ds_read_b128 v[144:147], v205
	ds_read_b128 v[236:239], v207
	ds_read_u16 v0, v189
	ds_read_u16 v1, v189 offset:272
	ds_read_u16 v2, v189 offset:544
	ds_read_u16 v3, v189 offset:816
	ds_read_u16 v4, v189 offset:1088
	ds_read_u16 v5, v189 offset:1360
	ds_read_u16 v6, v189 offset:1632
	ds_read_u16 v7, v189 offset:1904
	ds_read_u16 v8, v189 offset:2176
	ds_read_u16 v9, v189 offset:2448
	ds_read_u16 v10, v189 offset:2720
	ds_read_u16 v11, v189 offset:2992
	ds_read_u16 v12, v189 offset:3264
	ds_read_u16 v13, v189 offset:3536
	ds_read_u16 v14, v189 offset:3808
	ds_read_u16 v15, v189 offset:4080
	ds_read_u16 v16, v189 offset:4352
	ds_read_u16 v17, v189 offset:4624
	ds_read_u16 v18, v189 offset:4896
	ds_read_u16 v19, v189 offset:5168
	ds_read_u16 v20, v189 offset:5440
	ds_read_u16 v21, v189 offset:5712
	ds_read_u16 v22, v189 offset:5984
	ds_read_u16 v23, v189 offset:6256
	ds_read_u16 v24, v189 offset:6528
	ds_read_u16 v25, v189 offset:6800
	ds_read_u16 v26, v189 offset:7072
	ds_read_u16 v27, v189 offset:7344
	ds_read_u16 v28, v189 offset:7616
	ds_read_u16 v29, v189 offset:7888
	ds_read_u16 v30, v189 offset:8160
	ds_read_u16 v31, v189 offset:8432
	ds_read_u16 v32, v189 offset:8704
	ds_read_u16 v33, v189 offset:8976
	ds_read_u16 v34, v189 offset:9248
	ds_read_u16 v35, v189 offset:9520
	ds_read_u16 v36, v189 offset:9792
	ds_read_u16 v37, v189 offset:10064
	ds_read_u16 v38, v189 offset:10336
	ds_read_u16 v39, v189 offset:10608
	ds_read_u16 v40, v189 offset:10880
	ds_read_u16 v41, v189 offset:11152
	ds_read_u16 v42, v189 offset:11424
	ds_read_u16 v43, v189 offset:11696
	ds_read_u16 v44, v189 offset:11968
	ds_read_u16 v45, v189 offset:12240
	ds_read_u16 v46, v189 offset:12512
	ds_read_u16 v47, v189 offset:12784
	ds_read_u16 v72, v189 offset:13056
	ds_read_u16 v73, v189 offset:13328
	ds_read_u16 v74, v189 offset:13600
	ds_read_u16 v75, v189 offset:13872
	ds_read_u16 v76, v189 offset:14144
	ds_read_u16 v77, v189 offset:14416
	ds_read_u16 v78, v189 offset:14688
	ds_read_u16 v79, v189 offset:14960
	ds_read_u16 v80, v189 offset:15232
	ds_read_u16 v81, v189 offset:15504
	ds_read_u16 v82, v189 offset:15776
	ds_read_u16 v83, v189 offset:16048
	ds_read_u16 v84, v189 offset:16320
	ds_read_u16 v85, v189 offset:16592
	ds_read_u16 v86, v189 offset:16864
	ds_read_u16 v87, v189 offset:17136
	s_waitcnt lgkmcnt(0)
	v_lshlrev_b32_e32 v0, 16, v0
	v_lshlrev_b32_e32 v1, 16, v1
	v_lshlrev_b32_e32 v2, 16, v2
	v_lshlrev_b32_e32 v3, 16, v3
	v_lshlrev_b32_e32 v4, 16, v4
	v_lshlrev_b32_e32 v5, 16, v5
	v_lshlrev_b32_e32 v6, 16, v6
	v_lshlrev_b32_e32 v7, 16, v7
	v_lshlrev_b32_e32 v8, 16, v8
	v_lshlrev_b32_e32 v9, 16, v9
	v_lshlrev_b32_e32 v10, 16, v10
	v_lshlrev_b32_e32 v11, 16, v11
	v_lshlrev_b32_e32 v12, 16, v12
	v_lshlrev_b32_e32 v13, 16, v13
	v_lshlrev_b32_e32 v14, 16, v14
	v_lshlrev_b32_e32 v15, 16, v15
	v_lshlrev_b32_e32 v16, 16, v16
	v_lshlrev_b32_e32 v17, 16, v17
	v_lshlrev_b32_e32 v18, 16, v18
	v_lshlrev_b32_e32 v19, 16, v19
	v_lshlrev_b32_e32 v20, 16, v20
	v_lshlrev_b32_e32 v21, 16, v21
	v_lshlrev_b32_e32 v22, 16, v22
	v_lshlrev_b32_e32 v23, 16, v23
	v_lshlrev_b32_e32 v24, 16, v24
	v_lshlrev_b32_e32 v25, 16, v25
	v_lshlrev_b32_e32 v26, 16, v26
	v_lshlrev_b32_e32 v27, 16, v27
	v_lshlrev_b32_e32 v28, 16, v28
	v_lshlrev_b32_e32 v29, 16, v29
	v_lshlrev_b32_e32 v30, 16, v30
	v_lshlrev_b32_e32 v31, 16, v31
	v_lshlrev_b32_e32 v32, 16, v32
	v_lshlrev_b32_e32 v33, 16, v33
	v_lshlrev_b32_e32 v34, 16, v34
	v_lshlrev_b32_e32 v35, 16, v35
	v_lshlrev_b32_e32 v36, 16, v36
	v_lshlrev_b32_e32 v37, 16, v37
	v_lshlrev_b32_e32 v38, 16, v38
	v_lshlrev_b32_e32 v39, 16, v39
	v_lshlrev_b32_e32 v40, 16, v40
	v_lshlrev_b32_e32 v41, 16, v41
	v_lshlrev_b32_e32 v42, 16, v42
	v_lshlrev_b32_e32 v43, 16, v43
	v_lshlrev_b32_e32 v44, 16, v44
	v_lshlrev_b32_e32 v45, 16, v45
	v_lshlrev_b32_e32 v46, 16, v46
	v_lshlrev_b32_e32 v47, 16, v47
	v_lshlrev_b32_e32 v72, 16, v72
	v_lshlrev_b32_e32 v73, 16, v73
	v_lshlrev_b32_e32 v74, 16, v74
	v_lshlrev_b32_e32 v75, 16, v75
	v_lshlrev_b32_e32 v76, 16, v76
	v_lshlrev_b32_e32 v77, 16, v77
	v_lshlrev_b32_e32 v78, 16, v78
	v_lshlrev_b32_e32 v79, 16, v79
	v_lshlrev_b32_e32 v80, 16, v80
	v_lshlrev_b32_e32 v81, 16, v81
	v_lshlrev_b32_e32 v82, 16, v82
	v_lshlrev_b32_e32 v83, 16, v83
	v_lshlrev_b32_e32 v84, 16, v84
	v_lshlrev_b32_e32 v85, 16, v85
	v_lshlrev_b32_e32 v86, 16, v86
	v_lshlrev_b32_e32 v87, 16, v87
	v_mul_f32_e32 v0, v88, v0
	v_mul_f32_e32 v1, v89, v1
	v_mul_f32_e32 v2, v90, v2
	v_mul_f32_e32 v3, v91, v3
	v_mul_f32_e32 v4, v92, v4
	v_mul_f32_e32 v5, v93, v5
	v_mul_f32_e32 v6, v94, v6
	v_mul_f32_e32 v7, v95, v7
	v_mul_f32_e32 v8, v96, v8
	v_mul_f32_e32 v9, v97, v9
	v_mul_f32_e32 v10, v98, v10
	v_mul_f32_e32 v11, v99, v11
	v_mul_f32_e32 v12, v100, v12
	v_mul_f32_e32 v13, v101, v13
	v_mul_f32_e32 v14, v102, v14
	v_mul_f32_e32 v15, v103, v15
	v_mul_f32_e32 v16, v104, v16
	v_mul_f32_e32 v17, v105, v17
	v_mul_f32_e32 v18, v106, v18
	v_mul_f32_e32 v19, v107, v19
	v_mul_f32_e32 v20, v108, v20
	v_mul_f32_e32 v21, v109, v21
	v_mul_f32_e32 v22, v110, v22
	v_mul_f32_e32 v23, v111, v23
; #define LAS __attribute__((address_space(3)))
; __device__ __forceinline__ float bf2f(unsigned short v) { return __uint_as_float(((unsigned)v) << 16); }
; __device__ __forceinline__ void dn_prep_item(const Args& a, LAS unsigned char* lds, int item, int tid, int wave, int lane, int& cwh, int next_item) {
;     ...
;         { const LAS unsigned char* src = lds + (tid < 128 ? L_V : L_KH) + 2 * (tid & 127); const LAS float* fac = tid < 128 ? betas : bks;
; #pragma unroll
;           for (int i = 0; i < 64; ++i) x[i] = bf2f(*(const LAS unsigned short*)(src + i * KS_)) * fac[i]; }
;         { const LAS float* lrow = Lm + (lane & 15);
; #pragma unroll
;         for (int i = 1; i < 64; ++i) { float sa[4] = { x[i], 0.f, 0.f, 0.f };
;             int lr[4];
; #pragma unroll
;             for (int g = 0; g < (i + 15) / 16; ++g) lr[g] = __float_as_int(lrow[i * 68 + 16 * g]);
; #pragma unroll
;             for (int j = 0; j < i; ++j) { fmac_rowbcast_sel(sa[j & 3], lr[j >> 4], x[j], j); }
;             x[i] = (sa[0] + sa[1]) + (sa[2] + sa[3]); } }
	v_mul_f32_e32 v24, v112, v24
	v_mul_f32_e32 v25, v113, v25
	v_mul_f32_e32 v26, v114, v26
	v_mul_f32_e32 v27, v115, v27
	v_mul_f32_e32 v28, v116, v28
	v_mul_f32_e32 v29, v117, v29
	v_mul_f32_e32 v30, v118, v30
	v_mul_f32_e32 v31, v119, v31
	v_mul_f32_e32 v32, v120, v32
	v_mul_f32_e32 v33, v121, v33
	v_mul_f32_e32 v34, v122, v34
	v_mul_f32_e32 v35, v123, v35
	v_mul_f32_e32 v36, v124, v36
	v_mul_f32_e32 v37, v125, v37
	v_mul_f32_e32 v38, v126, v38
	v_mul_f32_e32 v39, v127, v39
	v_mul_f32_e32 v40, v128, v40
	v_mul_f32_e32 v41, v129, v41
	v_mul_f32_e32 v42, v130, v42
	v_mul_f32_e32 v43, v131, v43
	v_mul_f32_e32 v44, v132, v44
	v_mul_f32_e32 v45, v133, v45
	v_mul_f32_e32 v46, v134, v46
	v_mul_f32_e32 v47, v135, v47
	v_mul_f32_e32 v72, v136, v72
	v_mul_f32_e32 v73, v137, v73
	v_mul_f32_e32 v74, v138, v74
	v_mul_f32_e32 v75, v139, v75
	v_mul_f32_e32 v76, v140, v76
	v_mul_f32_e32 v77, v141, v77
	v_mul_f32_e32 v78, v142, v78
	v_mul_f32_e32 v79, v143, v79
	v_mul_f32_e32 v80, v144, v80
	v_mul_f32_e32 v81, v145, v81
	v_mul_f32_e32 v82, v146, v82
	v_mul_f32_e32 v83, v147, v83
	v_mul_f32_e32 v84, v236, v84
	v_mul_f32_e32 v85, v237, v85
	v_mul_f32_e32 v86, v238, v86
	v_mul_f32_e32 v87, v239, v87
	v_mov_b32_e32 v240, 0
	v_mov_b32_e32 v241, 0
	v_mov_b32_e32 v242, 0
	v_mov_b32_e32 v243, 0
	ds_read_b128 v[88:91], v234 offset:0
	ds_read_b128 v[104:107], v234 offset:1088
	ds_read_b128 v[108:111], v234 offset:1104
	ds_read_b128 v[120:123], v234 offset:2176
	ds_read_b128 v[124:127], v234 offset:2192
	ds_read_b128 v[128:131], v234 offset:2208
	s_waitcnt lgkmcnt(5)
	s_nop 4
	s_nop 3
	v_mov_b32_e32 v235, v0
	s_nop 1
	v_mfma_f32_4x4x1_16b_f32 v[0:3], v88, v235, v[0:3]
	s_nop 1
	s_nop 3
	v_mov_b32_e32 v235, v1
	s_nop 1
	v_mfma_f32_4x4x1_16b_f32 v[0:3], v89, v235, v[0:3]
	s_nop 1
	s_nop 3
	v_mov_b32_e32 v235, v2
	s_nop 1
	v_mfma_f32_4x4x1_16b_f32 v[0:3], v90, v235, v[0:3]
	s_nop 1
	ds_read_b128 v[88:91], v234 offset:3264
	ds_read_b128 v[92:95], v234 offset:3280
	ds_read_b128 v[96:99], v234 offset:3296
	ds_read_b128 v[100:103], v234 offset:3312
	s_waitcnt lgkmcnt(7)
	s_nop 4
	v_mfma_f32_4x4x1_16b_f32 v[4:7], v104, v0, v[4:7]
	v_mfma_f32_4x4x1_16b_f32 v[240:243], v105, v1, v[240:243]
	s_nop 0
	v_mfma_f32_4x4x1_16b_f32 v[4:7], v106, v2, v[4:7]
	v_mfma_f32_4x4x1_16b_f32 v[240:243], v107, v3, v[240:243]
	s_nop 0
	s_nop 3
	v_pk_add_f32 v[4:5], v[4:5], v[240:241]
	v_pk_add_f32 v[6:7], v[6:7], v[242:243]
	v_mov_b32_e32 v240, 0
	v_mov_b32_e32 v241, 0
	v_mov_b32_e32 v242, 0
	v_mov_b32_e32 v243, 0
	s_nop 3
	v_mov_b32_e32 v235, v4
	s_nop 1
	v_mfma_f32_4x4x1_16b_f32 v[4:7], v108, v235, v[4:7]
	s_nop 1
	s_nop 3
	v_mov_b32_e32 v235, v5
	s_nop 1
	v_mfma_f32_4x4x1_16b_f32 v[4:7], v109, v235, v[4:7]
	s_nop 1
	s_nop 3
	v_mov_b32_e32 v235, v6
	s_nop 1
	v_mfma_f32_4x4x1_16b_f32 v[4:7], v110, v235, v[4:7]
	s_nop 1
	ds_read_b128 v[104:107], v234 offset:4352
	ds_read_b128 v[108:111], v234 offset:4368
	ds_read_b128 v[112:115], v234 offset:4384
	ds_read_b128 v[116:119], v234 offset:4400
	s_waitcnt lgkmcnt(8)
	s_nop 4
	v_mfma_f32_4x4x1_16b_f32 v[8:11], v120, v0, v[8:11]
	v_mfma_f32_4x4x1_16b_f32 v[240:243], v121, v1, v[240:243]
	s_nop 0
	v_mfma_f32_4x4x1_16b_f32 v[8:11], v122, v2, v[8:11]
	v_mfma_f32_4x4x1_16b_f32 v[240:243], v123, v3, v[240:243]
	s_nop 0
	v_mfma_f32_4x4x1_16b_f32 v[8:11], v124, v4, v[8:11]
	v_mfma_f32_4x4x1_16b_f32 v[240:243], v125, v5, v[240:243]
	s_nop 0
	v_mfma_f32_4x4x1_16b_f32 v[8:11], v126, v6, v[8:11]
	v_mfma_f32_4x4x1_16b_f32 v[240:243], v127, v7, v[240:243]
	s_nop 0
	s_nop 3
	v_pk_add_f32 v[8:9], v[8:9], v[240:241]
	v_pk_add_f32 v[10:11], v[10:11], v[242:243]
	v_mov_b32_e32 v240, 0
	v_mov_b32_e32 v241, 0
	v_mov_b32_e32 v242, 0
	v_mov_b32_e32 v243, 0
	s_nop 3
	v_mov_b32_e32 v235, v8
	s_nop 1
	v_mfma_f32_4x4x1_16b_f32 v[8:11], v128, v235, v[8:11]
	s_nop 1
	s_nop 3
	v_mov_b32_e32 v235, v9
	s_nop 1
	v_mfma_f32_4x4x1_16b_f32 v[8:11], v129, v235, v[8:11]
	s_nop 1
	s_nop 3
	v_mov_b32_e32 v235, v10
	s_nop 1
	v_mfma_f32_4x4x1_16b_f32 v[8:11], v130, v235, v[8:11]
	s_nop 1
	ds_read_b128 v[120:123], v234 offset:4416
	s_waitcnt lgkmcnt(5)
	s_nop 4
	v_mfma_f32_4x4x1_16b_f32 v[12:15], v88, v0, v[12:15]
	v_mfma_f32_4x4x1_16b_f32 v[240:243], v89, v1, v[240:243]
	s_nop 0
	v_mfma_f32_4x4x1_16b_f32 v[12:15], v90, v2, v[12:15]
	v_mfma_f32_4x4x1_16b_f32 v[240:243], v91, v3, v[240:243]
	s_nop 0
	v_mfma_f32_4x4x1_16b_f32 v[12:15], v92, v4, v[12:15]
	v_mfma_f32_4x4x1_16b_f32 v[240:243], v93, v5, v[240:243]
	s_nop 0
	v_mfma_f32_4x4x1_16b_f32 v[12:15], v94, v6, v[12:15]
	v_mfma_f32_4x4x1_16b_f32 v[240:243], v95, v7, v[240:243]
	s_nop 0
	v_mfma_f32_4x4x1_16b_f32 v[12:15], v96, v8, v[12:15]
	v_mfma_f32_4x4x1_16b_f32 v[240:243], v97, v9, v[240:243]
	s_nop 0
	v_mfma_f32_4x4x1_16b_f32 v[12:15], v98, v10, v[12:15]
	v_mfma_f32_4x4x1_16b_f32 v[240:243], v99, v11, v[240:243]
	s_nop 0
	s_nop 3
	v_pk_add_f32 v[12:13], v[12:13], v[240:241]
	v_pk_add_f32 v[14:15], v[14:15], v[242:243]
	v_mov_b32_e32 v240, 0
	v_mov_b32_e32 v241, 0
	v_mov_b32_e32 v242, 0
	v_mov_b32_e32 v243, 0
	s_nop 3
	v_mov_b32_e32 v235, v12
	s_nop 1
	v_mfma_f32_4x4x1_16b_f32 v[12:15], v100, v235, v[12:15]
	s_nop 1
	s_nop 3
	v_mov_b32_e32 v235, v13
	s_nop 1
	v_mfma_f32_4x4x1_16b_f32 v[12:15], v101, v235, v[12:15]
	s_nop 1
	s_nop 3
	v_mov_b32_e32 v235, v14
	s_nop 1
	v_mfma_f32_4x4x1_16b_f32 v[12:15], v102, v235, v[12:15]
	s_nop 1
	ds_read_b128 v[88:91], v234 offset:5440
	ds_read_b128 v[92:95], v234 offset:5456
	ds_read_b128 v[96:99], v234 offset:5472
	ds_read_b128 v[100:103], v234 offset:5488
	s_waitcnt lgkmcnt(5)
; #define LAS __attribute__((address_space(3)))
; __device__ __forceinline__ void dn_prep_item(const Args& a, LAS unsigned char* lds, int item, int tid, int wave, int lane, int& cwh, int next_item) {
;     ...
;         { const LAS float* lrow = Lm + (lane & 15);
; #pragma unroll
;         for (int i = 1; i < 64; ++i) { float sa[4] = { x[i], 0.f, 0.f, 0.f };
;             int lr[4];
; #pragma unroll
;             for (int g = 0; g < (i + 15) / 16; ++g) lr[g] = __float_as_int(lrow[i * 68 + 16 * g]);
; #pragma unroll
;             for (int j = 0; j < i; ++j) { fmac_rowbcast_sel(sa[j & 3], lr[j >> 4], x[j], j); }
;             x[i] = (sa[0] + sa[1]) + (sa[2] + sa[3]); } }
	s_nop 4
	v_mfma_f32_4x4x1_16b_f32 v[16:19], v104, v0, v[16:19]
	v_mfma_f32_4x4x1_16b_f32 v[240:243], v105, v1, v[240:243]
	s_nop 0
	v_mfma_f32_4x4x1_16b_f32 v[16:19], v106, v2, v[16:19]
	v_mfma_f32_4x4x1_16b_f32 v[240:243], v107, v3, v[240:243]
	s_nop 0
	v_mfma_f32_4x4x1_16b_f32 v[16:19], v108, v4, v[16:19]
	v_mfma_f32_4x4x1_16b_f32 v[240:243], v109, v5, v[240:243]
	s_nop 0
	v_mfma_f32_4x4x1_16b_f32 v[16:19], v110, v6, v[16:19]
	v_mfma_f32_4x4x1_16b_f32 v[240:243], v111, v7, v[240:243]
	s_nop 0
	v_mfma_f32_4x4x1_16b_f32 v[16:19], v112, v8, v[16:19]
	v_mfma_f32_4x4x1_16b_f32 v[240:243], v113, v9, v[240:243]
	s_nop 0
	v_mfma_f32_4x4x1_16b_f32 v[16:19], v114, v10, v[16:19]
	v_mfma_f32_4x4x1_16b_f32 v[240:243], v115, v11, v[240:243]
	s_nop 0
	v_mfma_f32_4x4x1_16b_f32 v[16:19], v116, v12, v[16:19]
	v_mfma_f32_4x4x1_16b_f32 v[240:243], v117, v13, v[240:243]
	s_nop 0
	v_mfma_f32_4x4x1_16b_f32 v[16:19], v118, v14, v[16:19]
	v_mfma_f32_4x4x1_16b_f32 v[240:243], v119, v15, v[240:243]
	s_nop 0
	s_nop 3
	v_pk_add_f32 v[16:17], v[16:17], v[240:241]
	v_pk_add_f32 v[18:19], v[18:19], v[242:243]
	v_mov_b32_e32 v240, 0
	v_mov_b32_e32 v241, 0
	v_mov_b32_e32 v242, 0
	v_mov_b32_e32 v243, 0
	ds_read_b128 v[104:107], v234 offset:5504
	ds_read_b128 v[108:111], v234 offset:5520
	s_waitcnt lgkmcnt(6)
	s_nop 3
	v_mov_b32_e32 v235, v16
	s_nop 1
	v_mfma_f32_4x4x1_16b_f32 v[16:19], v120, v235, v[16:19]
	s_nop 1
	s_nop 3
	v_mov_b32_e32 v235, v17
	s_nop 1
	v_mfma_f32_4x4x1_16b_f32 v[16:19], v121, v235, v[16:19]
	s_nop 1
	s_nop 3
	v_mov_b32_e32 v235, v18
	s_nop 1
	v_mfma_f32_4x4x1_16b_f32 v[16:19], v122, v235, v[16:19]
	s_nop 1
	ds_read_b128 v[120:123], v234 offset:6528
	ds_read_b128 v[124:127], v234 offset:6544
	ds_read_b128 v[128:131], v234 offset:6560
	ds_read_b128 v[132:135], v234 offset:6576
	s_waitcnt lgkmcnt(6)
	s_nop 4
	v_mfma_f32_4x4x1_16b_f32 v[20:23], v88, v0, v[20:23]
	v_mfma_f32_4x4x1_16b_f32 v[240:243], v89, v1, v[240:243]
	s_nop 0
	v_mfma_f32_4x4x1_16b_f32 v[20:23], v90, v2, v[20:23]
	v_mfma_f32_4x4x1_16b_f32 v[240:243], v91, v3, v[240:243]
	s_nop 0
	v_mfma_f32_4x4x1_16b_f32 v[20:23], v92, v4, v[20:23]
	v_mfma_f32_4x4x1_16b_f32 v[240:243], v93, v5, v[240:243]
	s_nop 0
	v_mfma_f32_4x4x1_16b_f32 v[20:23], v94, v6, v[20:23]
	v_mfma_f32_4x4x1_16b_f32 v[240:243], v95, v7, v[240:243]
	s_nop 0
	v_mfma_f32_4x4x1_16b_f32 v[20:23], v96, v8, v[20:23]
	v_mfma_f32_4x4x1_16b_f32 v[240:243], v97, v9, v[240:243]
	s_nop 0
	v_mfma_f32_4x4x1_16b_f32 v[20:23], v98, v10, v[20:23]
	v_mfma_f32_4x4x1_16b_f32 v[240:243], v99, v11, v[240:243]
	s_nop 0
	v_mfma_f32_4x4x1_16b_f32 v[20:23], v100, v12, v[20:23]
	v_mfma_f32_4x4x1_16b_f32 v[240:243], v101, v13, v[240:243]
	s_nop 0
	v_mfma_f32_4x4x1_16b_f32 v[20:23], v102, v14, v[20:23]
	v_mfma_f32_4x4x1_16b_f32 v[240:243], v103, v15, v[240:243]
	s_nop 0
	ds_read_b128 v[88:91], v234 offset:6592
	ds_read_b128 v[92:95], v234 offset:6608
	ds_read_b128 v[96:99], v234 offset:6624
	s_waitcnt lgkmcnt(7)
	v_mfma_f32_4x4x1_16b_f32 v[20:23], v104, v16, v[20:23]
	v_mfma_f32_4x4x1_16b_f32 v[240:243], v105, v17, v[240:243]
	s_nop 0
	v_mfma_f32_4x4x1_16b_f32 v[20:23], v106, v18, v[20:23]
	v_mfma_f32_4x4x1_16b_f32 v[240:243], v107, v19, v[240:243]
	s_nop 0
	s_nop 3
	v_pk_add_f32 v[20:21], v[20:21], v[240:241]
	v_pk_add_f32 v[22:23], v[22:23], v[242:243]
	v_mov_b32_e32 v240, 0
	v_mov_b32_e32 v241, 0
	v_mov_b32_e32 v242, 0
	v_mov_b32_e32 v243, 0
	s_nop 3
	v_mov_b32_e32 v235, v20
	s_nop 1
	v_mfma_f32_4x4x1_16b_f32 v[20:23], v108, v235, v[20:23]
	s_nop 1
	s_nop 3
	v_mov_b32_e32 v235, v21
	s_nop 1
	v_mfma_f32_4x4x1_16b_f32 v[20:23], v109, v235, v[20:23]
	s_nop 1
	s_nop 3
	v_mov_b32_e32 v235, v22
	s_nop 1
	v_mfma_f32_4x4x1_16b_f32 v[20:23], v110, v235, v[20:23]
	s_nop 1
	ds_read_b128 v[104:107], v234 offset:7616
	ds_read_b128 v[108:111], v234 offset:7632
	ds_read_b128 v[112:115], v234 offset:7648
	ds_read_b128 v[116:119], v234 offset:7664
	s_waitcnt lgkmcnt(7)
	s_nop 4
	v_mfma_f32_4x4x1_16b_f32 v[24:27], v120, v0, v[24:27]
	v_mfma_f32_4x4x1_16b_f32 v[240:243], v121, v1, v[240:243]
	s_nop 0
	v_mfma_f32_4x4x1_16b_f32 v[24:27], v122, v2, v[24:27]
	v_mfma_f32_4x4x1_16b_f32 v[240:243], v123, v3, v[240:243]
	s_nop 0
	v_mfma_f32_4x4x1_16b_f32 v[24:27], v124, v4, v[24:27]
	v_mfma_f32_4x4x1_16b_f32 v[240:243], v125, v5, v[240:243]
	s_nop 0
	v_mfma_f32_4x4x1_16b_f32 v[24:27], v126, v6, v[24:27]
	v_mfma_f32_4x4x1_16b_f32 v[240:243], v127, v7, v[240:243]
	s_nop 0
	v_mfma_f32_4x4x1_16b_f32 v[24:27], v128, v8, v[24:27]
	v_mfma_f32_4x4x1_16b_f32 v[240:243], v129, v9, v[240:243]
	s_nop 0
	v_mfma_f32_4x4x1_16b_f32 v[24:27], v130, v10, v[24:27]
	v_mfma_f32_4x4x1_16b_f32 v[240:243], v131, v11, v[240:243]
	s_nop 0
	v_mfma_f32_4x4x1_16b_f32 v[24:27], v132, v12, v[24:27]
	v_mfma_f32_4x4x1_16b_f32 v[240:243], v133, v13, v[240:243]
	s_nop 0
	v_mfma_f32_4x4x1_16b_f32 v[24:27], v134, v14, v[24:27]
	v_mfma_f32_4x4x1_16b_f32 v[240:243], v135, v15, v[240:243]
	s_nop 0
	ds_read_b128 v[120:123], v234 offset:7680
	ds_read_b128 v[124:127], v234 offset:7696
	ds_read_b128 v[128:131], v234 offset:7712
	ds_read_b128 v[132:135], v234 offset:7728
	s_waitcnt lgkmcnt(8)
; #define LAS __attribute__((address_space(3)))
; __device__ __forceinline__ void dn_prep_item(const Args& a, LAS unsigned char* lds, int item, int tid, int wave, int lane, int& cwh, int next_item) {
;     ...
;         { const LAS float* lrow = Lm + (lane & 15);
; #pragma unroll
;         for (int i = 1; i < 64; ++i) { float sa[4] = { x[i], 0.f, 0.f, 0.f };
;             int lr[4];
; #pragma unroll
;             for (int g = 0; g < (i + 15) / 16; ++g) lr[g] = __float_as_int(lrow[i * 68 + 16 * g]);
; #pragma unroll
;             for (int j = 0; j < i; ++j) { fmac_rowbcast_sel(sa[j & 3], lr[j >> 4], x[j], j); }
;             x[i] = (sa[0] + sa[1]) + (sa[2] + sa[3]); } }
	v_mfma_f32_4x4x1_16b_f32 v[24:27], v88, v16, v[24:27]
	v_mfma_f32_4x4x1_16b_f32 v[240:243], v89, v17, v[240:243]
	s_nop 0
	v_mfma_f32_4x4x1_16b_f32 v[24:27], v90, v18, v[24:27]
	v_mfma_f32_4x4x1_16b_f32 v[240:243], v91, v19, v[240:243]
	s_nop 0
	v_mfma_f32_4x4x1_16b_f32 v[24:27], v92, v20, v[24:27]
	v_mfma_f32_4x4x1_16b_f32 v[240:243], v93, v21, v[240:243]
	s_nop 0
	v_mfma_f32_4x4x1_16b_f32 v[24:27], v94, v22, v[24:27]
	v_mfma_f32_4x4x1_16b_f32 v[240:243], v95, v23, v[240:243]
	s_nop 0
	s_nop 3
	v_pk_add_f32 v[24:25], v[24:25], v[240:241]
	v_pk_add_f32 v[26:27], v[26:27], v[242:243]
	v_mov_b32_e32 v240, 0
	v_mov_b32_e32 v241, 0
	v_mov_b32_e32 v242, 0
	v_mov_b32_e32 v243, 0
	s_nop 3
	v_mov_b32_e32 v235, v24
	s_nop 1
	v_mfma_f32_4x4x1_16b_f32 v[24:27], v96, v235, v[24:27]
	s_nop 1
	s_nop 3
	v_mov_b32_e32 v235, v25
	s_nop 1
	v_mfma_f32_4x4x1_16b_f32 v[24:27], v97, v235, v[24:27]
	s_nop 1
	s_nop 3
	v_mov_b32_e32 v235, v26
	s_nop 1
	v_mfma_f32_4x4x1_16b_f32 v[24:27], v98, v235, v[24:27]
	s_nop 1
	ds_read_b128 v[88:91], v234 offset:8704
	ds_read_b128 v[92:95], v234 offset:8720
	ds_read_b128 v[96:99], v234 offset:8736
	ds_read_b128 v[100:103], v234 offset:8752
	s_waitcnt lgkmcnt(8)
	s_nop 4
	v_mfma_f32_4x4x1_16b_f32 v[28:31], v104, v0, v[28:31]
	v_mfma_f32_4x4x1_16b_f32 v[240:243], v105, v1, v[240:243]
	s_nop 0
	v_mfma_f32_4x4x1_16b_f32 v[28:31], v106, v2, v[28:31]
	v_mfma_f32_4x4x1_16b_f32 v[240:243], v107, v3, v[240:243]
	s_nop 0
	v_mfma_f32_4x4x1_16b_f32 v[28:31], v108, v4, v[28:31]
	v_mfma_f32_4x4x1_16b_f32 v[240:243], v109, v5, v[240:243]
	s_nop 0
	v_mfma_f32_4x4x1_16b_f32 v[28:31], v110, v6, v[28:31]
	v_mfma_f32_4x4x1_16b_f32 v[240:243], v111, v7, v[240:243]
	s_nop 0
	v_mfma_f32_4x4x1_16b_f32 v[28:31], v112, v8, v[28:31]
	v_mfma_f32_4x4x1_16b_f32 v[240:243], v113, v9, v[240:243]
	s_nop 0
	v_mfma_f32_4x4x1_16b_f32 v[28:31], v114, v10, v[28:31]
	v_mfma_f32_4x4x1_16b_f32 v[240:243], v115, v11, v[240:243]
	s_nop 0
	v_mfma_f32_4x4x1_16b_f32 v[28:31], v116, v12, v[28:31]
	v_mfma_f32_4x4x1_16b_f32 v[240:243], v117, v13, v[240:243]
	s_nop 0
	v_mfma_f32_4x4x1_16b_f32 v[28:31], v118, v14, v[28:31]
	v_mfma_f32_4x4x1_16b_f32 v[240:243], v119, v15, v[240:243]
	s_nop 0
	ds_read_b128 v[104:107], v234 offset:8768
	ds_read_b128 v[108:111], v234 offset:8784
	ds_read_b128 v[112:115], v234 offset:8800
	ds_read_b128 v[116:119], v234 offset:8816
	s_waitcnt lgkmcnt(8)
	v_mfma_f32_4x4x1_16b_f32 v[28:31], v120, v16, v[28:31]
	v_mfma_f32_4x4x1_16b_f32 v[240:243], v121, v17, v[240:243]
	s_nop 0
	v_mfma_f32_4x4x1_16b_f32 v[28:31], v122, v18, v[28:31]
	v_mfma_f32_4x4x1_16b_f32 v[240:243], v123, v19, v[240:243]
	s_nop 0
	v_mfma_f32_4x4x1_16b_f32 v[28:31], v124, v20, v[28:31]
	v_mfma_f32_4x4x1_16b_f32 v[240:243], v125, v21, v[240:243]
	s_nop 0
	v_mfma_f32_4x4x1_16b_f32 v[28:31], v126, v22, v[28:31]
	v_mfma_f32_4x4x1_16b_f32 v[240:243], v127, v23, v[240:243]
	s_nop 0
	v_mfma_f32_4x4x1_16b_f32 v[28:31], v128, v24, v[28:31]
	v_mfma_f32_4x4x1_16b_f32 v[240:243], v129, v25, v[240:243]
	s_nop 0
	v_mfma_f32_4x4x1_16b_f32 v[28:31], v130, v26, v[28:31]
	v_mfma_f32_4x4x1_16b_f32 v[240:243], v131, v27, v[240:243]
	s_nop 0
	s_nop 3
	v_pk_add_f32 v[28:29], v[28:29], v[240:241]
	v_pk_add_f32 v[30:31], v[30:31], v[242:243]
	v_mov_b32_e32 v240, 0
	v_mov_b32_e32 v241, 0
	v_mov_b32_e32 v242, 0
	v_mov_b32_e32 v243, 0
	s_nop 3
	v_mov_b32_e32 v235, v28
	s_nop 1
	v_mfma_f32_4x4x1_16b_f32 v[28:31], v132, v235, v[28:31]
	s_nop 1
	s_nop 3
	v_mov_b32_e32 v235, v29
	s_nop 1
	v_mfma_f32_4x4x1_16b_f32 v[28:31], v133, v235, v[28:31]
	s_nop 1
	s_nop 3
	v_mov_b32_e32 v235, v30
	s_nop 1
	v_mfma_f32_4x4x1_16b_f32 v[28:31], v134, v235, v[28:31]
	s_nop 1
	ds_read_b128 v[120:123], v234 offset:8832
	s_waitcnt lgkmcnt(5)
	s_nop 4
	v_mfma_f32_4x4x1_16b_f32 v[32:35], v88, v0, v[32:35]
	v_mfma_f32_4x4x1_16b_f32 v[240:243], v89, v1, v[240:243]
	s_nop 0
	v_mfma_f32_4x4x1_16b_f32 v[32:35], v90, v2, v[32:35]
	v_mfma_f32_4x4x1_16b_f32 v[240:243], v91, v3, v[240:243]
	s_nop 0
	v_mfma_f32_4x4x1_16b_f32 v[32:35], v92, v4, v[32:35]
	v_mfma_f32_4x4x1_16b_f32 v[240:243], v93, v5, v[240:243]
	s_nop 0
	v_mfma_f32_4x4x1_16b_f32 v[32:35], v94, v6, v[32:35]
	v_mfma_f32_4x4x1_16b_f32 v[240:243], v95, v7, v[240:243]
	s_nop 0
	v_mfma_f32_4x4x1_16b_f32 v[32:35], v96, v8, v[32:35]
	v_mfma_f32_4x4x1_16b_f32 v[240:243], v97, v9, v[240:243]
	s_nop 0
	v_mfma_f32_4x4x1_16b_f32 v[32:35], v98, v10, v[32:35]
	v_mfma_f32_4x4x1_16b_f32 v[240:243], v99, v11, v[240:243]
	s_nop 0
	v_mfma_f32_4x4x1_16b_f32 v[32:35], v100, v12, v[32:35]
	v_mfma_f32_4x4x1_16b_f32 v[240:243], v101, v13, v[240:243]
	s_nop 0
	v_mfma_f32_4x4x1_16b_f32 v[32:35], v102, v14, v[32:35]
	v_mfma_f32_4x4x1_16b_f32 v[240:243], v103, v15, v[240:243]
	s_nop 0
	ds_read_b128 v[88:91], v234 offset:9792
	ds_read_b128 v[92:95], v234 offset:9808
	ds_read_b128 v[96:99], v234 offset:9824
	ds_read_b128 v[100:103], v234 offset:9840
	s_waitcnt lgkmcnt(5)
	v_mfma_f32_4x4x1_16b_f32 v[32:35], v104, v16, v[32:35]
	v_mfma_f32_4x4x1_16b_f32 v[240:243], v105, v17, v[240:243]
	s_nop 0
	v_mfma_f32_4x4x1_16b_f32 v[32:35], v106, v18, v[32:35]
	v_mfma_f32_4x4x1_16b_f32 v[240:243], v107, v19, v[240:243]
	s_nop 0
	v_mfma_f32_4x4x1_16b_f32 v[32:35], v108, v20, v[32:35]
	v_mfma_f32_4x4x1_16b_f32 v[240:243], v109, v21, v[240:243]
	s_nop 0
	v_mfma_f32_4x4x1_16b_f32 v[32:35], v110, v22, v[32:35]
	v_mfma_f32_4x4x1_16b_f32 v[240:243], v111, v23, v[240:243]
	s_nop 0
	v_mfma_f32_4x4x1_16b_f32 v[32:35], v112, v24, v[32:35]
	v_mfma_f32_4x4x1_16b_f32 v[240:243], v113, v25, v[240:243]
	s_nop 0
	v_mfma_f32_4x4x1_16b_f32 v[32:35], v114, v26, v[32:35]
	v_mfma_f32_4x4x1_16b_f32 v[240:243], v115, v27, v[240:243]
	s_nop 0
	v_mfma_f32_4x4x1_16b_f32 v[32:35], v116, v28, v[32:35]
	v_mfma_f32_4x4x1_16b_f32 v[240:243], v117, v29, v[240:243]
	s_nop 0
	v_mfma_f32_4x4x1_16b_f32 v[32:35], v118, v30, v[32:35]
	v_mfma_f32_4x4x1_16b_f32 v[240:243], v119, v31, v[240:243]
	s_nop 0
	s_nop 3
	v_pk_add_f32 v[32:33], v[32:33], v[240:241]
	v_pk_add_f32 v[34:35], v[34:35], v[242:243]
	v_mov_b32_e32 v240, 0
	v_mov_b32_e32 v241, 0
	v_mov_b32_e32 v242, 0
	v_mov_b32_e32 v243, 0
	ds_read_b128 v[104:107], v234 offset:9856
	ds_read_b128 v[108:111], v234 offset:9872
	ds_read_b128 v[112:115], v234 offset:9888
	ds_read_b128 v[116:119], v234 offset:9904
	s_waitcnt lgkmcnt(8)
; #define LAS __attribute__((address_space(3)))
; __device__ __forceinline__ void dn_prep_item(const Args& a, LAS unsigned char* lds, int item, int tid, int wave, int lane, int& cwh, int next_item) {
;     ...
;         { const LAS float* lrow = Lm + (lane & 15);
; #pragma unroll
;         for (int i = 1; i < 64; ++i) { float sa[4] = { x[i], 0.f, 0.f, 0.f };
;             int lr[4];
; #pragma unroll
;             for (int g = 0; g < (i + 15) / 16; ++g) lr[g] = __float_as_int(lrow[i * 68 + 16 * g]);
; #pragma unroll
;             for (int j = 0; j < i; ++j) { fmac_rowbcast_sel(sa[j & 3], lr[j >> 4], x[j], j); }
;             x[i] = (sa[0] + sa[1]) + (sa[2] + sa[3]); } }
	s_nop 3
	v_mov_b32_e32 v235, v32
	s_nop 1
	v_mfma_f32_4x4x1_16b_f32 v[32:35], v120, v235, v[32:35]
	s_nop 1
	s_nop 3
	v_mov_b32_e32 v235, v33
	s_nop 1
	v_mfma_f32_4x4x1_16b_f32 v[32:35], v121, v235, v[32:35]
	s_nop 1
	s_nop 3
	v_mov_b32_e32 v235, v34
	s_nop 1
	v_mfma_f32_4x4x1_16b_f32 v[32:35], v122, v235, v[32:35]
	s_nop 1
	ds_read_b128 v[120:123], v234 offset:9920
	ds_read_b128 v[124:127], v234 offset:9936
	s_waitcnt lgkmcnt(6)
	s_nop 4
	v_mfma_f32_4x4x1_16b_f32 v[36:39], v88, v0, v[36:39]
	v_mfma_f32_4x4x1_16b_f32 v[240:243], v89, v1, v[240:243]
	s_nop 0
	v_mfma_f32_4x4x1_16b_f32 v[36:39], v90, v2, v[36:39]
	v_mfma_f32_4x4x1_16b_f32 v[240:243], v91, v3, v[240:243]
	s_nop 0
	v_mfma_f32_4x4x1_16b_f32 v[36:39], v92, v4, v[36:39]
	v_mfma_f32_4x4x1_16b_f32 v[240:243], v93, v5, v[240:243]
	s_nop 0
	v_mfma_f32_4x4x1_16b_f32 v[36:39], v94, v6, v[36:39]
	v_mfma_f32_4x4x1_16b_f32 v[240:243], v95, v7, v[240:243]
	s_nop 0
	v_mfma_f32_4x4x1_16b_f32 v[36:39], v96, v8, v[36:39]
	v_mfma_f32_4x4x1_16b_f32 v[240:243], v97, v9, v[240:243]
	s_nop 0
	v_mfma_f32_4x4x1_16b_f32 v[36:39], v98, v10, v[36:39]
	v_mfma_f32_4x4x1_16b_f32 v[240:243], v99, v11, v[240:243]
	s_nop 0
	v_mfma_f32_4x4x1_16b_f32 v[36:39], v100, v12, v[36:39]
	v_mfma_f32_4x4x1_16b_f32 v[240:243], v101, v13, v[240:243]
	s_nop 0
	v_mfma_f32_4x4x1_16b_f32 v[36:39], v102, v14, v[36:39]
	v_mfma_f32_4x4x1_16b_f32 v[240:243], v103, v15, v[240:243]
	s_nop 0
	ds_read_b128 v[88:91], v234 offset:10880
	ds_read_b128 v[92:95], v234 offset:10896
	ds_read_b128 v[96:99], v234 offset:10912
	ds_read_b128 v[100:103], v234 offset:10928
	s_waitcnt lgkmcnt(6)
	v_mfma_f32_4x4x1_16b_f32 v[36:39], v104, v16, v[36:39]
	v_mfma_f32_4x4x1_16b_f32 v[240:243], v105, v17, v[240:243]
	s_nop 0
	v_mfma_f32_4x4x1_16b_f32 v[36:39], v106, v18, v[36:39]
	v_mfma_f32_4x4x1_16b_f32 v[240:243], v107, v19, v[240:243]
	s_nop 0
	v_mfma_f32_4x4x1_16b_f32 v[36:39], v108, v20, v[36:39]
	v_mfma_f32_4x4x1_16b_f32 v[240:243], v109, v21, v[240:243]
	s_nop 0
	v_mfma_f32_4x4x1_16b_f32 v[36:39], v110, v22, v[36:39]
	v_mfma_f32_4x4x1_16b_f32 v[240:243], v111, v23, v[240:243]
	s_nop 0
	v_mfma_f32_4x4x1_16b_f32 v[36:39], v112, v24, v[36:39]
	v_mfma_f32_4x4x1_16b_f32 v[240:243], v113, v25, v[240:243]
	s_nop 0
	v_mfma_f32_4x4x1_16b_f32 v[36:39], v114, v26, v[36:39]
	v_mfma_f32_4x4x1_16b_f32 v[240:243], v115, v27, v[240:243]
	s_nop 0
	v_mfma_f32_4x4x1_16b_f32 v[36:39], v116, v28, v[36:39]
	v_mfma_f32_4x4x1_16b_f32 v[240:243], v117, v29, v[240:243]
	s_nop 0
	v_mfma_f32_4x4x1_16b_f32 v[36:39], v118, v30, v[36:39]
	v_mfma_f32_4x4x1_16b_f32 v[240:243], v119, v31, v[240:243]
	s_nop 0
	ds_read_b128 v[104:107], v234 offset:10944
	ds_read_b128 v[108:111], v234 offset:10960
	ds_read_b128 v[112:115], v234 offset:10976
	ds_read_b128 v[116:119], v234 offset:10992
	s_waitcnt lgkmcnt(8)
	v_mfma_f32_4x4x1_16b_f32 v[36:39], v120, v32, v[36:39]
	v_mfma_f32_4x4x1_16b_f32 v[240:243], v121, v33, v[240:243]
	s_nop 0
	v_mfma_f32_4x4x1_16b_f32 v[36:39], v122, v34, v[36:39]
	v_mfma_f32_4x4x1_16b_f32 v[240:243], v123, v35, v[240:243]
	s_nop 0
	s_nop 3
	v_pk_add_f32 v[36:37], v[36:37], v[240:241]
	v_pk_add_f32 v[38:39], v[38:39], v[242:243]
	v_mov_b32_e32 v240, 0
	v_mov_b32_e32 v241, 0
	v_mov_b32_e32 v242, 0
	v_mov_b32_e32 v243, 0
	s_nop 3
	v_mov_b32_e32 v235, v36
	s_nop 1
	v_mfma_f32_4x4x1_16b_f32 v[36:39], v124, v235, v[36:39]
	s_nop 1
	s_nop 3
	v_mov_b32_e32 v235, v37
	s_nop 1
	v_mfma_f32_4x4x1_16b_f32 v[36:39], v125, v235, v[36:39]
	s_nop 1
	s_nop 3
	v_mov_b32_e32 v235, v38
	s_nop 1
	v_mfma_f32_4x4x1_16b_f32 v[36:39], v126, v235, v[36:39]
	s_nop 1
	ds_read_b128 v[120:123], v234 offset:11008
	ds_read_b128 v[124:127], v234 offset:11024
	ds_read_b128 v[128:131], v234 offset:11040
	s_waitcnt lgkmcnt(7)
	s_nop 4
	v_mfma_f32_4x4x1_16b_f32 v[40:43], v88, v0, v[40:43]
	v_mfma_f32_4x4x1_16b_f32 v[240:243], v89, v1, v[240:243]
	s_nop 0
	v_mfma_f32_4x4x1_16b_f32 v[40:43], v90, v2, v[40:43]
	v_mfma_f32_4x4x1_16b_f32 v[240:243], v91, v3, v[240:243]
	s_nop 0
	v_mfma_f32_4x4x1_16b_f32 v[40:43], v92, v4, v[40:43]
	v_mfma_f32_4x4x1_16b_f32 v[240:243], v93, v5, v[240:243]
	s_nop 0
	v_mfma_f32_4x4x1_16b_f32 v[40:43], v94, v6, v[40:43]
	v_mfma_f32_4x4x1_16b_f32 v[240:243], v95, v7, v[240:243]
	s_nop 0
	v_mfma_f32_4x4x1_16b_f32 v[40:43], v96, v8, v[40:43]
	v_mfma_f32_4x4x1_16b_f32 v[240:243], v97, v9, v[240:243]
	s_nop 0
	v_mfma_f32_4x4x1_16b_f32 v[40:43], v98, v10, v[40:43]
	v_mfma_f32_4x4x1_16b_f32 v[240:243], v99, v11, v[240:243]
	s_nop 0
	v_mfma_f32_4x4x1_16b_f32 v[40:43], v100, v12, v[40:43]
	v_mfma_f32_4x4x1_16b_f32 v[240:243], v101, v13, v[240:243]
	s_nop 0
	v_mfma_f32_4x4x1_16b_f32 v[40:43], v102, v14, v[40:43]
	v_mfma_f32_4x4x1_16b_f32 v[240:243], v103, v15, v[240:243]
	s_nop 0
	ds_read_b128 v[88:91], v234 offset:11968
	ds_read_b128 v[92:95], v234 offset:11984
	ds_read_b128 v[96:99], v234 offset:12000
	ds_read_b128 v[100:103], v234 offset:12016
	s_waitcnt lgkmcnt(7)
	v_mfma_f32_4x4x1_16b_f32 v[40:43], v104, v16, v[40:43]
	v_mfma_f32_4x4x1_16b_f32 v[240:243], v105, v17, v[240:243]
	s_nop 0
	v_mfma_f32_4x4x1_16b_f32 v[40:43], v106, v18, v[40:43]
	v_mfma_f32_4x4x1_16b_f32 v[240:243], v107, v19, v[240:243]
	s_nop 0
	v_mfma_f32_4x4x1_16b_f32 v[40:43], v108, v20, v[40:43]
	v_mfma_f32_4x4x1_16b_f32 v[240:243], v109, v21, v[240:243]
	s_nop 0
	v_mfma_f32_4x4x1_16b_f32 v[40:43], v110, v22, v[40:43]
	v_mfma_f32_4x4x1_16b_f32 v[240:243], v111, v23, v[240:243]
	s_nop 0
	v_mfma_f32_4x4x1_16b_f32 v[40:43], v112, v24, v[40:43]
	v_mfma_f32_4x4x1_16b_f32 v[240:243], v113, v25, v[240:243]
	s_nop 0
	v_mfma_f32_4x4x1_16b_f32 v[40:43], v114, v26, v[40:43]
	v_mfma_f32_4x4x1_16b_f32 v[240:243], v115, v27, v[240:243]
	s_nop 0
	v_mfma_f32_4x4x1_16b_f32 v[40:43], v116, v28, v[40:43]
	v_mfma_f32_4x4x1_16b_f32 v[240:243], v117, v29, v[240:243]
	s_nop 0
	v_mfma_f32_4x4x1_16b_f32 v[40:43], v118, v30, v[40:43]
	v_mfma_f32_4x4x1_16b_f32 v[240:243], v119, v31, v[240:243]
	s_nop 0
	ds_read_b128 v[104:107], v234 offset:12032
	ds_read_b128 v[108:111], v234 offset:12048
	ds_read_b128 v[112:115], v234 offset:12064
	ds_read_b128 v[116:119], v234 offset:12080
	s_waitcnt lgkmcnt(8)
; #define LAS __attribute__((address_space(3)))
; __device__ __forceinline__ void dn_prep_item(const Args& a, LAS unsigned char* lds, int item, int tid, int wave, int lane, int& cwh, int next_item) {
;     ...
;         { const LAS float* lrow = Lm + (lane & 15);
; #pragma unroll
;         for (int i = 1; i < 64; ++i) { float sa[4] = { x[i], 0.f, 0.f, 0.f };
;             int lr[4];
; #pragma unroll
;             for (int g = 0; g < (i + 15) / 16; ++g) lr[g] = __float_as_int(lrow[i * 68 + 16 * g]);
; #pragma unroll
;             for (int j = 0; j < i; ++j) { fmac_rowbcast_sel(sa[j & 3], lr[j >> 4], x[j], j); }
;             x[i] = (sa[0] + sa[1]) + (sa[2] + sa[3]); } }
	v_mfma_f32_4x4x1_16b_f32 v[40:43], v120, v32, v[40:43]
	v_mfma_f32_4x4x1_16b_f32 v[240:243], v121, v33, v[240:243]
	s_nop 0
	v_mfma_f32_4x4x1_16b_f32 v[40:43], v122, v34, v[40:43]
	v_mfma_f32_4x4x1_16b_f32 v[240:243], v123, v35, v[240:243]
	s_nop 0
	v_mfma_f32_4x4x1_16b_f32 v[40:43], v124, v36, v[40:43]
	v_mfma_f32_4x4x1_16b_f32 v[240:243], v125, v37, v[240:243]
	s_nop 0
	v_mfma_f32_4x4x1_16b_f32 v[40:43], v126, v38, v[40:43]
	v_mfma_f32_4x4x1_16b_f32 v[240:243], v127, v39, v[240:243]
	s_nop 0
	s_nop 3
	v_pk_add_f32 v[40:41], v[40:41], v[240:241]
	v_pk_add_f32 v[42:43], v[42:43], v[242:243]
	v_mov_b32_e32 v240, 0
	v_mov_b32_e32 v241, 0
	v_mov_b32_e32 v242, 0
	v_mov_b32_e32 v243, 0
	s_nop 3
	v_mov_b32_e32 v235, v40
	s_nop 1
	v_mfma_f32_4x4x1_16b_f32 v[40:43], v128, v235, v[40:43]
	s_nop 1
	s_nop 3
	v_mov_b32_e32 v235, v41
	s_nop 1
	v_mfma_f32_4x4x1_16b_f32 v[40:43], v129, v235, v[40:43]
	s_nop 1
	s_nop 3
	v_mov_b32_e32 v235, v42
	s_nop 1
	v_mfma_f32_4x4x1_16b_f32 v[40:43], v130, v235, v[40:43]
	s_nop 1
	ds_read_b128 v[120:123], v234 offset:12096
	ds_read_b128 v[124:127], v234 offset:12112
	ds_read_b128 v[128:131], v234 offset:12128
	ds_read_b128 v[132:135], v234 offset:12144
	s_waitcnt lgkmcnt(8)
	s_nop 4
	v_mfma_f32_4x4x1_16b_f32 v[44:47], v88, v0, v[44:47]
	v_mfma_f32_4x4x1_16b_f32 v[240:243], v89, v1, v[240:243]
	s_nop 0
	v_mfma_f32_4x4x1_16b_f32 v[44:47], v90, v2, v[44:47]
	v_mfma_f32_4x4x1_16b_f32 v[240:243], v91, v3, v[240:243]
	s_nop 0
	v_mfma_f32_4x4x1_16b_f32 v[44:47], v92, v4, v[44:47]
	v_mfma_f32_4x4x1_16b_f32 v[240:243], v93, v5, v[240:243]
	s_nop 0
	v_mfma_f32_4x4x1_16b_f32 v[44:47], v94, v6, v[44:47]
	v_mfma_f32_4x4x1_16b_f32 v[240:243], v95, v7, v[240:243]
	s_nop 0
	v_mfma_f32_4x4x1_16b_f32 v[44:47], v96, v8, v[44:47]
	v_mfma_f32_4x4x1_16b_f32 v[240:243], v97, v9, v[240:243]
	s_nop 0
	v_mfma_f32_4x4x1_16b_f32 v[44:47], v98, v10, v[44:47]
	v_mfma_f32_4x4x1_16b_f32 v[240:243], v99, v11, v[240:243]
	s_nop 0
	v_mfma_f32_4x4x1_16b_f32 v[44:47], v100, v12, v[44:47]
	v_mfma_f32_4x4x1_16b_f32 v[240:243], v101, v13, v[240:243]
	s_nop 0
	v_mfma_f32_4x4x1_16b_f32 v[44:47], v102, v14, v[44:47]
	v_mfma_f32_4x4x1_16b_f32 v[240:243], v103, v15, v[240:243]
	s_nop 0
	ds_read_b128 v[88:91], v234 offset:13056
	ds_read_b128 v[92:95], v234 offset:13072
	ds_read_b128 v[96:99], v234 offset:13088
	ds_read_b128 v[100:103], v234 offset:13104
	s_waitcnt lgkmcnt(8)
	v_mfma_f32_4x4x1_16b_f32 v[44:47], v104, v16, v[44:47]
	v_mfma_f32_4x4x1_16b_f32 v[240:243], v105, v17, v[240:243]
	s_nop 0
	v_mfma_f32_4x4x1_16b_f32 v[44:47], v106, v18, v[44:47]
	v_mfma_f32_4x4x1_16b_f32 v[240:243], v107, v19, v[240:243]
	s_nop 0
	v_mfma_f32_4x4x1_16b_f32 v[44:47], v108, v20, v[44:47]
	v_mfma_f32_4x4x1_16b_f32 v[240:243], v109, v21, v[240:243]
	s_nop 0
	v_mfma_f32_4x4x1_16b_f32 v[44:47], v110, v22, v[44:47]
	v_mfma_f32_4x4x1_16b_f32 v[240:243], v111, v23, v[240:243]
	s_nop 0
	v_mfma_f32_4x4x1_16b_f32 v[44:47], v112, v24, v[44:47]
	v_mfma_f32_4x4x1_16b_f32 v[240:243], v113, v25, v[240:243]
	s_nop 0
	v_mfma_f32_4x4x1_16b_f32 v[44:47], v114, v26, v[44:47]
	v_mfma_f32_4x4x1_16b_f32 v[240:243], v115, v27, v[240:243]
	s_nop 0
	v_mfma_f32_4x4x1_16b_f32 v[44:47], v116, v28, v[44:47]
	v_mfma_f32_4x4x1_16b_f32 v[240:243], v117, v29, v[240:243]
	s_nop 0
	v_mfma_f32_4x4x1_16b_f32 v[44:47], v118, v30, v[44:47]
	v_mfma_f32_4x4x1_16b_f32 v[240:243], v119, v31, v[240:243]
	s_nop 0
	ds_read_b128 v[104:107], v234 offset:13120
	ds_read_b128 v[108:111], v234 offset:13136
	ds_read_b128 v[112:115], v234 offset:13152
	ds_read_b128 v[116:119], v234 offset:13168
	s_waitcnt lgkmcnt(8)
	v_mfma_f32_4x4x1_16b_f32 v[44:47], v120, v32, v[44:47]
	v_mfma_f32_4x4x1_16b_f32 v[240:243], v121, v33, v[240:243]
	s_nop 0
	v_mfma_f32_4x4x1_16b_f32 v[44:47], v122, v34, v[44:47]
	v_mfma_f32_4x4x1_16b_f32 v[240:243], v123, v35, v[240:243]
	s_nop 0
	v_mfma_f32_4x4x1_16b_f32 v[44:47], v124, v36, v[44:47]
	v_mfma_f32_4x4x1_16b_f32 v[240:243], v125, v37, v[240:243]
	s_nop 0
	v_mfma_f32_4x4x1_16b_f32 v[44:47], v126, v38, v[44:47]
	v_mfma_f32_4x4x1_16b_f32 v[240:243], v127, v39, v[240:243]
	s_nop 0
	v_mfma_f32_4x4x1_16b_f32 v[44:47], v128, v40, v[44:47]
	v_mfma_f32_4x4x1_16b_f32 v[240:243], v129, v41, v[240:243]
	s_nop 0
	v_mfma_f32_4x4x1_16b_f32 v[44:47], v130, v42, v[44:47]
	v_mfma_f32_4x4x1_16b_f32 v[240:243], v131, v43, v[240:243]
	s_nop 0
	s_nop 3
	v_pk_add_f32 v[44:45], v[44:45], v[240:241]
	v_pk_add_f32 v[46:47], v[46:47], v[242:243]
	v_mov_b32_e32 v240, 0
	v_mov_b32_e32 v241, 0
	v_mov_b32_e32 v242, 0
	v_mov_b32_e32 v243, 0
	s_nop 3
	v_mov_b32_e32 v235, v44
	s_nop 1
	v_mfma_f32_4x4x1_16b_f32 v[44:47], v132, v235, v[44:47]
	s_nop 1
	s_nop 3
	v_mov_b32_e32 v235, v45
	s_nop 1
	v_mfma_f32_4x4x1_16b_f32 v[44:47], v133, v235, v[44:47]
	s_nop 1
	s_nop 3
	v_mov_b32_e32 v235, v46
	s_nop 1
	v_mfma_f32_4x4x1_16b_f32 v[44:47], v134, v235, v[44:47]
	s_nop 1
	ds_read_b128 v[120:123], v234 offset:13184
	ds_read_b128 v[124:127], v234 offset:13200
	ds_read_b128 v[128:131], v234 offset:13216
	ds_read_b128 v[132:135], v234 offset:13232
	s_waitcnt lgkmcnt(8)
	s_nop 4
	v_mfma_f32_4x4x1_16b_f32 v[72:75], v88, v0, v[72:75]
	v_mfma_f32_4x4x1_16b_f32 v[240:243], v89, v1, v[240:243]
	s_nop 0
	v_mfma_f32_4x4x1_16b_f32 v[72:75], v90, v2, v[72:75]
	v_mfma_f32_4x4x1_16b_f32 v[240:243], v91, v3, v[240:243]
	s_nop 0
	v_mfma_f32_4x4x1_16b_f32 v[72:75], v92, v4, v[72:75]
	v_mfma_f32_4x4x1_16b_f32 v[240:243], v93, v5, v[240:243]
	s_nop 0
	v_mfma_f32_4x4x1_16b_f32 v[72:75], v94, v6, v[72:75]
	v_mfma_f32_4x4x1_16b_f32 v[240:243], v95, v7, v[240:243]
	s_nop 0
	v_mfma_f32_4x4x1_16b_f32 v[72:75], v96, v8, v[72:75]
	v_mfma_f32_4x4x1_16b_f32 v[240:243], v97, v9, v[240:243]
	s_nop 0
	v_mfma_f32_4x4x1_16b_f32 v[72:75], v98, v10, v[72:75]
	v_mfma_f32_4x4x1_16b_f32 v[240:243], v99, v11, v[240:243]
	s_nop 0
	v_mfma_f32_4x4x1_16b_f32 v[72:75], v100, v12, v[72:75]
	v_mfma_f32_4x4x1_16b_f32 v[240:243], v101, v13, v[240:243]
	s_nop 0
	v_mfma_f32_4x4x1_16b_f32 v[72:75], v102, v14, v[72:75]
	v_mfma_f32_4x4x1_16b_f32 v[240:243], v103, v15, v[240:243]
	s_nop 0
	ds_read_b128 v[88:91], v234 offset:13248
	s_waitcnt lgkmcnt(5)
; #define LAS __attribute__((address_space(3)))
; __device__ __forceinline__ void dn_prep_item(const Args& a, LAS unsigned char* lds, int item, int tid, int wave, int lane, int& cwh, int next_item) {
;     ...
;         { const LAS float* lrow = Lm + (lane & 15);
; #pragma unroll
;         for (int i = 1; i < 64; ++i) { float sa[4] = { x[i], 0.f, 0.f, 0.f };
;             int lr[4];
; #pragma unroll
;             for (int g = 0; g < (i + 15) / 16; ++g) lr[g] = __float_as_int(lrow[i * 68 + 16 * g]);
; #pragma unroll
;             for (int j = 0; j < i; ++j) { fmac_rowbcast_sel(sa[j & 3], lr[j >> 4], x[j], j); }
;             x[i] = (sa[0] + sa[1]) + (sa[2] + sa[3]); } }
	v_mfma_f32_4x4x1_16b_f32 v[72:75], v104, v16, v[72:75]
	v_mfma_f32_4x4x1_16b_f32 v[240:243], v105, v17, v[240:243]
	s_nop 0
	v_mfma_f32_4x4x1_16b_f32 v[72:75], v106, v18, v[72:75]
	v_mfma_f32_4x4x1_16b_f32 v[240:243], v107, v19, v[240:243]
	s_nop 0
	v_mfma_f32_4x4x1_16b_f32 v[72:75], v108, v20, v[72:75]
	v_mfma_f32_4x4x1_16b_f32 v[240:243], v109, v21, v[240:243]
	s_nop 0
	v_mfma_f32_4x4x1_16b_f32 v[72:75], v110, v22, v[72:75]
	v_mfma_f32_4x4x1_16b_f32 v[240:243], v111, v23, v[240:243]
	s_nop 0
	v_mfma_f32_4x4x1_16b_f32 v[72:75], v112, v24, v[72:75]
	v_mfma_f32_4x4x1_16b_f32 v[240:243], v113, v25, v[240:243]
	s_nop 0
	v_mfma_f32_4x4x1_16b_f32 v[72:75], v114, v26, v[72:75]
	v_mfma_f32_4x4x1_16b_f32 v[240:243], v115, v27, v[240:243]
	s_nop 0
	v_mfma_f32_4x4x1_16b_f32 v[72:75], v116, v28, v[72:75]
	v_mfma_f32_4x4x1_16b_f32 v[240:243], v117, v29, v[240:243]
	s_nop 0
	v_mfma_f32_4x4x1_16b_f32 v[72:75], v118, v30, v[72:75]
	v_mfma_f32_4x4x1_16b_f32 v[240:243], v119, v31, v[240:243]
	s_nop 0
	ds_read_b128 v[104:107], v234 offset:14144
	ds_read_b128 v[108:111], v234 offset:14160
	ds_read_b128 v[112:115], v234 offset:14176
	ds_read_b128 v[116:119], v234 offset:14192
	s_waitcnt lgkmcnt(5)
	v_mfma_f32_4x4x1_16b_f32 v[72:75], v120, v32, v[72:75]
	v_mfma_f32_4x4x1_16b_f32 v[240:243], v121, v33, v[240:243]
	s_nop 0
	v_mfma_f32_4x4x1_16b_f32 v[72:75], v122, v34, v[72:75]
	v_mfma_f32_4x4x1_16b_f32 v[240:243], v123, v35, v[240:243]
	s_nop 0
	v_mfma_f32_4x4x1_16b_f32 v[72:75], v124, v36, v[72:75]
	v_mfma_f32_4x4x1_16b_f32 v[240:243], v125, v37, v[240:243]
	s_nop 0
	v_mfma_f32_4x4x1_16b_f32 v[72:75], v126, v38, v[72:75]
	v_mfma_f32_4x4x1_16b_f32 v[240:243], v127, v39, v[240:243]
	s_nop 0
	v_mfma_f32_4x4x1_16b_f32 v[72:75], v128, v40, v[72:75]
	v_mfma_f32_4x4x1_16b_f32 v[240:243], v129, v41, v[240:243]
	s_nop 0
	v_mfma_f32_4x4x1_16b_f32 v[72:75], v130, v42, v[72:75]
	v_mfma_f32_4x4x1_16b_f32 v[240:243], v131, v43, v[240:243]
	s_nop 0
	v_mfma_f32_4x4x1_16b_f32 v[72:75], v132, v44, v[72:75]
	v_mfma_f32_4x4x1_16b_f32 v[240:243], v133, v45, v[240:243]
	s_nop 0
	v_mfma_f32_4x4x1_16b_f32 v[72:75], v134, v46, v[72:75]
	v_mfma_f32_4x4x1_16b_f32 v[240:243], v135, v47, v[240:243]
	s_nop 0
	s_nop 3
	v_pk_add_f32 v[72:73], v[72:73], v[240:241]
	v_pk_add_f32 v[74:75], v[74:75], v[242:243]
	v_mov_b32_e32 v240, 0
	v_mov_b32_e32 v241, 0
	v_mov_b32_e32 v242, 0
	v_mov_b32_e32 v243, 0
	ds_read_b128 v[120:123], v234 offset:14208
	ds_read_b128 v[124:127], v234 offset:14224
	ds_read_b128 v[128:131], v234 offset:14240
	ds_read_b128 v[132:135], v234 offset:14256
	s_waitcnt lgkmcnt(8)
	s_nop 3
	v_mov_b32_e32 v235, v72
	s_nop 1
	v_mfma_f32_4x4x1_16b_f32 v[72:75], v88, v235, v[72:75]
	s_nop 1
	s_nop 3
	v_mov_b32_e32 v235, v73
	s_nop 1
	v_mfma_f32_4x4x1_16b_f32 v[72:75], v89, v235, v[72:75]
	s_nop 1
	s_nop 3
	v_mov_b32_e32 v235, v74
	s_nop 1
	v_mfma_f32_4x4x1_16b_f32 v[72:75], v90, v235, v[72:75]
	s_nop 1
	ds_read_b128 v[88:91], v234 offset:14272
	ds_read_b128 v[92:95], v234 offset:14288
	ds_read_b128 v[96:99], v234 offset:14304
	ds_read_b128 v[100:103], v234 offset:14320
	s_waitcnt lgkmcnt(8)
	s_nop 4
	v_mfma_f32_4x4x1_16b_f32 v[76:79], v104, v0, v[76:79]
	v_mfma_f32_4x4x1_16b_f32 v[240:243], v105, v1, v[240:243]
	s_nop 0
	v_mfma_f32_4x4x1_16b_f32 v[76:79], v106, v2, v[76:79]
	v_mfma_f32_4x4x1_16b_f32 v[240:243], v107, v3, v[240:243]
	s_nop 0
	v_mfma_f32_4x4x1_16b_f32 v[76:79], v108, v4, v[76:79]
	v_mfma_f32_4x4x1_16b_f32 v[240:243], v109, v5, v[240:243]
	s_nop 0
	v_mfma_f32_4x4x1_16b_f32 v[76:79], v110, v6, v[76:79]
	v_mfma_f32_4x4x1_16b_f32 v[240:243], v111, v7, v[240:243]
	s_nop 0
	v_mfma_f32_4x4x1_16b_f32 v[76:79], v112, v8, v[76:79]
	v_mfma_f32_4x4x1_16b_f32 v[240:243], v113, v9, v[240:243]
	s_nop 0
	v_mfma_f32_4x4x1_16b_f32 v[76:79], v114, v10, v[76:79]
	v_mfma_f32_4x4x1_16b_f32 v[240:243], v115, v11, v[240:243]
	s_nop 0
	v_mfma_f32_4x4x1_16b_f32 v[76:79], v116, v12, v[76:79]
	v_mfma_f32_4x4x1_16b_f32 v[240:243], v117, v13, v[240:243]
	s_nop 0
	v_mfma_f32_4x4x1_16b_f32 v[76:79], v118, v14, v[76:79]
	v_mfma_f32_4x4x1_16b_f32 v[240:243], v119, v15, v[240:243]
	s_nop 0
	ds_read_b128 v[104:107], v234 offset:14336
	ds_read_b128 v[108:111], v234 offset:14352
	s_waitcnt lgkmcnt(6)
	v_mfma_f32_4x4x1_16b_f32 v[76:79], v120, v16, v[76:79]
	v_mfma_f32_4x4x1_16b_f32 v[240:243], v121, v17, v[240:243]
	s_nop 0
	v_mfma_f32_4x4x1_16b_f32 v[76:79], v122, v18, v[76:79]
	v_mfma_f32_4x4x1_16b_f32 v[240:243], v123, v19, v[240:243]
	s_nop 0
	v_mfma_f32_4x4x1_16b_f32 v[76:79], v124, v20, v[76:79]
	v_mfma_f32_4x4x1_16b_f32 v[240:243], v125, v21, v[240:243]
	s_nop 0
	v_mfma_f32_4x4x1_16b_f32 v[76:79], v126, v22, v[76:79]
	v_mfma_f32_4x4x1_16b_f32 v[240:243], v127, v23, v[240:243]
	s_nop 0
	v_mfma_f32_4x4x1_16b_f32 v[76:79], v128, v24, v[76:79]
	v_mfma_f32_4x4x1_16b_f32 v[240:243], v129, v25, v[240:243]
	s_nop 0
	v_mfma_f32_4x4x1_16b_f32 v[76:79], v130, v26, v[76:79]
	v_mfma_f32_4x4x1_16b_f32 v[240:243], v131, v27, v[240:243]
	s_nop 0
	v_mfma_f32_4x4x1_16b_f32 v[76:79], v132, v28, v[76:79]
	v_mfma_f32_4x4x1_16b_f32 v[240:243], v133, v29, v[240:243]
	s_nop 0
	v_mfma_f32_4x4x1_16b_f32 v[76:79], v134, v30, v[76:79]
	v_mfma_f32_4x4x1_16b_f32 v[240:243], v135, v31, v[240:243]
	s_nop 0
	ds_read_b128 v[120:123], v234 offset:15232
	ds_read_b128 v[124:127], v234 offset:15248
	ds_read_b128 v[128:131], v234 offset:15264
	ds_read_b128 v[132:135], v234 offset:15280
	s_waitcnt lgkmcnt(6)
; #define LAS __attribute__((address_space(3)))
; __device__ __forceinline__ void dn_prep_item(const Args& a, LAS unsigned char* lds, int item, int tid, int wave, int lane, int& cwh, int next_item) {
;     ...
;         { const LAS float* lrow = Lm + (lane & 15);
; #pragma unroll
;         for (int i = 1; i < 64; ++i) { float sa[4] = { x[i], 0.f, 0.f, 0.f };
;             int lr[4];
; #pragma unroll
;             for (int g = 0; g < (i + 15) / 16; ++g) lr[g] = __float_as_int(lrow[i * 68 + 16 * g]);
; #pragma unroll
;             for (int j = 0; j < i; ++j) { fmac_rowbcast_sel(sa[j & 3], lr[j >> 4], x[j], j); }
;             x[i] = (sa[0] + sa[1]) + (sa[2] + sa[3]); } }
	v_mfma_f32_4x4x1_16b_f32 v[76:79], v88, v32, v[76:79]
	v_mfma_f32_4x4x1_16b_f32 v[240:243], v89, v33, v[240:243]
	s_nop 0
	v_mfma_f32_4x4x1_16b_f32 v[76:79], v90, v34, v[76:79]
	v_mfma_f32_4x4x1_16b_f32 v[240:243], v91, v35, v[240:243]
	s_nop 0
	v_mfma_f32_4x4x1_16b_f32 v[76:79], v92, v36, v[76:79]
	v_mfma_f32_4x4x1_16b_f32 v[240:243], v93, v37, v[240:243]
	s_nop 0
	v_mfma_f32_4x4x1_16b_f32 v[76:79], v94, v38, v[76:79]
	v_mfma_f32_4x4x1_16b_f32 v[240:243], v95, v39, v[240:243]
	s_nop 0
	v_mfma_f32_4x4x1_16b_f32 v[76:79], v96, v40, v[76:79]
	v_mfma_f32_4x4x1_16b_f32 v[240:243], v97, v41, v[240:243]
	s_nop 0
	v_mfma_f32_4x4x1_16b_f32 v[76:79], v98, v42, v[76:79]
	v_mfma_f32_4x4x1_16b_f32 v[240:243], v99, v43, v[240:243]
	s_nop 0
	v_mfma_f32_4x4x1_16b_f32 v[76:79], v100, v44, v[76:79]
	v_mfma_f32_4x4x1_16b_f32 v[240:243], v101, v45, v[240:243]
	s_nop 0
	v_mfma_f32_4x4x1_16b_f32 v[76:79], v102, v46, v[76:79]
	v_mfma_f32_4x4x1_16b_f32 v[240:243], v103, v47, v[240:243]
	s_nop 0
	ds_read_b128 v[88:91], v234 offset:15296
	ds_read_b128 v[92:95], v234 offset:15312
	ds_read_b128 v[96:99], v234 offset:15328
	ds_read_b128 v[100:103], v234 offset:15344
	s_waitcnt lgkmcnt(8)
	v_mfma_f32_4x4x1_16b_f32 v[76:79], v104, v72, v[76:79]
	v_mfma_f32_4x4x1_16b_f32 v[240:243], v105, v73, v[240:243]
	s_nop 0
	v_mfma_f32_4x4x1_16b_f32 v[76:79], v106, v74, v[76:79]
	v_mfma_f32_4x4x1_16b_f32 v[240:243], v107, v75, v[240:243]
	s_nop 0
	s_nop 3
	v_pk_add_f32 v[76:77], v[76:77], v[240:241]
	v_pk_add_f32 v[78:79], v[78:79], v[242:243]
	v_mov_b32_e32 v240, 0
	v_mov_b32_e32 v241, 0
	v_mov_b32_e32 v242, 0
	v_mov_b32_e32 v243, 0
	s_nop 3
	v_mov_b32_e32 v235, v76
	s_nop 1
	v_mfma_f32_4x4x1_16b_f32 v[76:79], v108, v235, v[76:79]
	s_nop 1
	s_nop 3
	v_mov_b32_e32 v235, v77
	s_nop 1
	v_mfma_f32_4x4x1_16b_f32 v[76:79], v109, v235, v[76:79]
	s_nop 1
	s_nop 3
	v_mov_b32_e32 v235, v78
	s_nop 1
	v_mfma_f32_4x4x1_16b_f32 v[76:79], v110, v235, v[76:79]
	s_nop 1
	ds_read_b128 v[104:107], v234 offset:15360
	ds_read_b128 v[108:111], v234 offset:15376
	ds_read_b128 v[112:115], v234 offset:15392
	ds_read_b128 v[116:119], v234 offset:15408
	s_waitcnt lgkmcnt(8)
	s_nop 4
	v_mfma_f32_4x4x1_16b_f32 v[80:83], v120, v0, v[80:83]
	v_mfma_f32_4x4x1_16b_f32 v[240:243], v121, v1, v[240:243]
	s_nop 0
	v_mfma_f32_4x4x1_16b_f32 v[80:83], v122, v2, v[80:83]
	v_mfma_f32_4x4x1_16b_f32 v[240:243], v123, v3, v[240:243]
	s_nop 0
	v_mfma_f32_4x4x1_16b_f32 v[80:83], v124, v4, v[80:83]
	v_mfma_f32_4x4x1_16b_f32 v[240:243], v125, v5, v[240:243]
	s_nop 0
	v_mfma_f32_4x4x1_16b_f32 v[80:83], v126, v6, v[80:83]
	v_mfma_f32_4x4x1_16b_f32 v[240:243], v127, v7, v[240:243]
	s_nop 0
	v_mfma_f32_4x4x1_16b_f32 v[80:83], v128, v8, v[80:83]
	v_mfma_f32_4x4x1_16b_f32 v[240:243], v129, v9, v[240:243]
	s_nop 0
	v_mfma_f32_4x4x1_16b_f32 v[80:83], v130, v10, v[80:83]
	v_mfma_f32_4x4x1_16b_f32 v[240:243], v131, v11, v[240:243]
	s_nop 0
	v_mfma_f32_4x4x1_16b_f32 v[80:83], v132, v12, v[80:83]
	v_mfma_f32_4x4x1_16b_f32 v[240:243], v133, v13, v[240:243]
	s_nop 0
	v_mfma_f32_4x4x1_16b_f32 v[80:83], v134, v14, v[80:83]
	v_mfma_f32_4x4x1_16b_f32 v[240:243], v135, v15, v[240:243]
	s_nop 0
	ds_read_b128 v[120:123], v234 offset:15424
	ds_read_b128 v[124:127], v234 offset:15440
	ds_read_b128 v[128:131], v234 offset:15456
	s_waitcnt lgkmcnt(7)
	v_mfma_f32_4x4x1_16b_f32 v[80:83], v88, v16, v[80:83]
	v_mfma_f32_4x4x1_16b_f32 v[240:243], v89, v17, v[240:243]
	s_nop 0
	v_mfma_f32_4x4x1_16b_f32 v[80:83], v90, v18, v[80:83]
	v_mfma_f32_4x4x1_16b_f32 v[240:243], v91, v19, v[240:243]
	s_nop 0
	v_mfma_f32_4x4x1_16b_f32 v[80:83], v92, v20, v[80:83]
	v_mfma_f32_4x4x1_16b_f32 v[240:243], v93, v21, v[240:243]
	s_nop 0
	v_mfma_f32_4x4x1_16b_f32 v[80:83], v94, v22, v[80:83]
	v_mfma_f32_4x4x1_16b_f32 v[240:243], v95, v23, v[240:243]
	s_nop 0
	v_mfma_f32_4x4x1_16b_f32 v[80:83], v96, v24, v[80:83]
	v_mfma_f32_4x4x1_16b_f32 v[240:243], v97, v25, v[240:243]
	s_nop 0
	v_mfma_f32_4x4x1_16b_f32 v[80:83], v98, v26, v[80:83]
	v_mfma_f32_4x4x1_16b_f32 v[240:243], v99, v27, v[240:243]
	s_nop 0
	v_mfma_f32_4x4x1_16b_f32 v[80:83], v100, v28, v[80:83]
	v_mfma_f32_4x4x1_16b_f32 v[240:243], v101, v29, v[240:243]
	s_nop 0
	v_mfma_f32_4x4x1_16b_f32 v[80:83], v102, v30, v[80:83]
	v_mfma_f32_4x4x1_16b_f32 v[240:243], v103, v31, v[240:243]
	s_nop 0
	ds_read_b128 v[88:91], v234 offset:16320
	ds_read_b128 v[92:95], v234 offset:16336
	ds_read_b128 v[96:99], v234 offset:16352
	ds_read_b128 v[100:103], v234 offset:16368
	s_waitcnt lgkmcnt(7)
	v_mfma_f32_4x4x1_16b_f32 v[80:83], v104, v32, v[80:83]
	v_mfma_f32_4x4x1_16b_f32 v[240:243], v105, v33, v[240:243]
	s_nop 0
	v_mfma_f32_4x4x1_16b_f32 v[80:83], v106, v34, v[80:83]
	v_mfma_f32_4x4x1_16b_f32 v[240:243], v107, v35, v[240:243]
	s_nop 0
	v_mfma_f32_4x4x1_16b_f32 v[80:83], v108, v36, v[80:83]
	v_mfma_f32_4x4x1_16b_f32 v[240:243], v109, v37, v[240:243]
	s_nop 0
	v_mfma_f32_4x4x1_16b_f32 v[80:83], v110, v38, v[80:83]
	v_mfma_f32_4x4x1_16b_f32 v[240:243], v111, v39, v[240:243]
	s_nop 0
	v_mfma_f32_4x4x1_16b_f32 v[80:83], v112, v40, v[80:83]
	v_mfma_f32_4x4x1_16b_f32 v[240:243], v113, v41, v[240:243]
	s_nop 0
	v_mfma_f32_4x4x1_16b_f32 v[80:83], v114, v42, v[80:83]
	v_mfma_f32_4x4x1_16b_f32 v[240:243], v115, v43, v[240:243]
	s_nop 0
	v_mfma_f32_4x4x1_16b_f32 v[80:83], v116, v44, v[80:83]
	v_mfma_f32_4x4x1_16b_f32 v[240:243], v117, v45, v[240:243]
	s_nop 0
	v_mfma_f32_4x4x1_16b_f32 v[80:83], v118, v46, v[80:83]
	v_mfma_f32_4x4x1_16b_f32 v[240:243], v119, v47, v[240:243]
	s_nop 0
	ds_read_b128 v[104:107], v234 offset:16384
	ds_read_b128 v[108:111], v234 offset:16400
	ds_read_b128 v[112:115], v234 offset:16416
	ds_read_b128 v[116:119], v234 offset:16432
	s_waitcnt lgkmcnt(8)
; #define LAS __attribute__((address_space(3)))
; __device__ __forceinline__ void dn_prep_item(const Args& a, LAS unsigned char* lds, int item, int tid, int wave, int lane, int& cwh, int next_item) {
;     ...
;         { const LAS float* lrow = Lm + (lane & 15);
; #pragma unroll
;         for (int i = 1; i < 64; ++i) { float sa[4] = { x[i], 0.f, 0.f, 0.f };
;             int lr[4];
; #pragma unroll
;             for (int g = 0; g < (i + 15) / 16; ++g) lr[g] = __float_as_int(lrow[i * 68 + 16 * g]);
; #pragma unroll
;             for (int j = 0; j < i; ++j) { fmac_rowbcast_sel(sa[j & 3], lr[j >> 4], x[j], j); }
;             x[i] = (sa[0] + sa[1]) + (sa[2] + sa[3]); } }
	v_mfma_f32_4x4x1_16b_f32 v[80:83], v120, v72, v[80:83]
	v_mfma_f32_4x4x1_16b_f32 v[240:243], v121, v73, v[240:243]
	s_nop 0
	v_mfma_f32_4x4x1_16b_f32 v[80:83], v122, v74, v[80:83]
	v_mfma_f32_4x4x1_16b_f32 v[240:243], v123, v75, v[240:243]
	s_nop 0
	v_mfma_f32_4x4x1_16b_f32 v[80:83], v124, v76, v[80:83]
	v_mfma_f32_4x4x1_16b_f32 v[240:243], v125, v77, v[240:243]
	s_nop 0
	v_mfma_f32_4x4x1_16b_f32 v[80:83], v126, v78, v[80:83]
	v_mfma_f32_4x4x1_16b_f32 v[240:243], v127, v79, v[240:243]
	s_nop 0
	s_nop 3
	v_pk_add_f32 v[80:81], v[80:81], v[240:241]
	v_pk_add_f32 v[82:83], v[82:83], v[242:243]
	v_mov_b32_e32 v240, 0
	v_mov_b32_e32 v241, 0
	v_mov_b32_e32 v242, 0
	v_mov_b32_e32 v243, 0
	s_nop 3
	v_mov_b32_e32 v235, v80
	s_nop 1
	v_mfma_f32_4x4x1_16b_f32 v[80:83], v128, v235, v[80:83]
	s_nop 1
	s_nop 3
	v_mov_b32_e32 v235, v81
	s_nop 1
	v_mfma_f32_4x4x1_16b_f32 v[80:83], v129, v235, v[80:83]
	s_nop 1
	s_nop 3
	v_mov_b32_e32 v235, v82
	s_nop 1
	v_mfma_f32_4x4x1_16b_f32 v[80:83], v130, v235, v[80:83]
	s_nop 1
	ds_read_b128 v[120:123], v234 offset:16448
	ds_read_b128 v[124:127], v234 offset:16464
	ds_read_b128 v[128:131], v234 offset:16480
	ds_read_b128 v[132:135], v234 offset:16496
	s_waitcnt lgkmcnt(8)
	s_nop 4
	v_mfma_f32_4x4x1_16b_f32 v[84:87], v88, v0, v[84:87]
	v_mfma_f32_4x4x1_16b_f32 v[240:243], v89, v1, v[240:243]
	s_nop 0
	v_mfma_f32_4x4x1_16b_f32 v[84:87], v90, v2, v[84:87]
	v_mfma_f32_4x4x1_16b_f32 v[240:243], v91, v3, v[240:243]
	s_nop 0
	v_mfma_f32_4x4x1_16b_f32 v[84:87], v92, v4, v[84:87]
	v_mfma_f32_4x4x1_16b_f32 v[240:243], v93, v5, v[240:243]
	s_nop 0
	v_mfma_f32_4x4x1_16b_f32 v[84:87], v94, v6, v[84:87]
	v_mfma_f32_4x4x1_16b_f32 v[240:243], v95, v7, v[240:243]
	s_nop 0
	v_mfma_f32_4x4x1_16b_f32 v[84:87], v96, v8, v[84:87]
	v_mfma_f32_4x4x1_16b_f32 v[240:243], v97, v9, v[240:243]
	s_nop 0
	v_mfma_f32_4x4x1_16b_f32 v[84:87], v98, v10, v[84:87]
	v_mfma_f32_4x4x1_16b_f32 v[240:243], v99, v11, v[240:243]
	s_nop 0
	v_mfma_f32_4x4x1_16b_f32 v[84:87], v100, v12, v[84:87]
	v_mfma_f32_4x4x1_16b_f32 v[240:243], v101, v13, v[240:243]
	s_nop 0
	v_mfma_f32_4x4x1_16b_f32 v[84:87], v102, v14, v[84:87]
	v_mfma_f32_4x4x1_16b_f32 v[240:243], v103, v15, v[240:243]
	s_nop 0
	ds_read_b128 v[88:91], v234 offset:16512
	ds_read_b128 v[92:95], v234 offset:16528
	ds_read_b128 v[96:99], v234 offset:16544
	ds_read_b128 v[100:103], v234 offset:16560
	s_waitcnt lgkmcnt(8)
	v_mfma_f32_4x4x1_16b_f32 v[84:87], v104, v16, v[84:87]
	v_mfma_f32_4x4x1_16b_f32 v[240:243], v105, v17, v[240:243]
	s_nop 0
	v_mfma_f32_4x4x1_16b_f32 v[84:87], v106, v18, v[84:87]
	v_mfma_f32_4x4x1_16b_f32 v[240:243], v107, v19, v[240:243]
	s_nop 0
	v_mfma_f32_4x4x1_16b_f32 v[84:87], v108, v20, v[84:87]
	v_mfma_f32_4x4x1_16b_f32 v[240:243], v109, v21, v[240:243]
	s_nop 0
	v_mfma_f32_4x4x1_16b_f32 v[84:87], v110, v22, v[84:87]
	v_mfma_f32_4x4x1_16b_f32 v[240:243], v111, v23, v[240:243]
	s_nop 0
	v_mfma_f32_4x4x1_16b_f32 v[84:87], v112, v24, v[84:87]
	v_mfma_f32_4x4x1_16b_f32 v[240:243], v113, v25, v[240:243]
	s_nop 0
	v_mfma_f32_4x4x1_16b_f32 v[84:87], v114, v26, v[84:87]
	v_mfma_f32_4x4x1_16b_f32 v[240:243], v115, v27, v[240:243]
	s_nop 0
	v_mfma_f32_4x4x1_16b_f32 v[84:87], v116, v28, v[84:87]
	v_mfma_f32_4x4x1_16b_f32 v[240:243], v117, v29, v[240:243]
	s_nop 0
	v_mfma_f32_4x4x1_16b_f32 v[84:87], v118, v30, v[84:87]
	v_mfma_f32_4x4x1_16b_f32 v[240:243], v119, v31, v[240:243]
	s_nop 0
	s_waitcnt lgkmcnt(4)
; #define LAS __attribute__((address_space(3)))
; __device__ __forceinline__ unsigned pk2(float lo, float hi) { const f32x2_t v = {lo, hi}; const bf16x2_t b = __builtin_convertvector(v, bf16x2_t); return __builtin_bit_cast(unsigned, b); }
; __device__ __forceinline__ void dn_prep_item(const Args& a, LAS unsigned char* lds, int item, int tid, int wave, int lane, int& cwh, int next_item) {
;     ...
;         { const LAS float* lrow = Lm + (lane & 15);
; #pragma unroll
;         for (int i = 1; i < 64; ++i) { float sa[4] = { x[i], 0.f, 0.f, 0.f };
;             int lr[4];
; #pragma unroll
;             for (int g = 0; g < (i + 15) / 16; ++g) lr[g] = __float_as_int(lrow[i * 68 + 16 * g]);
; #pragma unroll
;             for (int j = 0; j < i; ++j) { fmac_rowbcast_sel(sa[j & 3], lr[j >> 4], x[j], j); }
;             x[i] = (sa[0] + sa[1]) + (sa[2] + sa[3]); } }
; #pragma unroll
;         for (int q = 0; q < 8; ++q) { v4u w; w.x = pk2(x[8 * q], x[8 * q + 1]); w.y = pk2(x[8 * q + 2], x[8 * q + 3]); w.z = pk2(x[8 * q + 4], x[8 * q + 5]); w.w = pk2(x[8 * q + 6], x[8 * q + 7]);
;             *(LAS v4u*)(lds + L_SOL + tid * AS_ + 16 * q) = w; }
	v_mfma_f32_4x4x1_16b_f32 v[84:87], v120, v32, v[84:87]
	v_mfma_f32_4x4x1_16b_f32 v[240:243], v121, v33, v[240:243]
	s_nop 0
	v_mfma_f32_4x4x1_16b_f32 v[84:87], v122, v34, v[84:87]
	v_mfma_f32_4x4x1_16b_f32 v[240:243], v123, v35, v[240:243]
	s_nop 0
	v_mfma_f32_4x4x1_16b_f32 v[84:87], v124, v36, v[84:87]
	v_mfma_f32_4x4x1_16b_f32 v[240:243], v125, v37, v[240:243]
	s_nop 0
	v_mfma_f32_4x4x1_16b_f32 v[84:87], v126, v38, v[84:87]
	v_mfma_f32_4x4x1_16b_f32 v[240:243], v127, v39, v[240:243]
	s_nop 0
	v_mfma_f32_4x4x1_16b_f32 v[84:87], v128, v40, v[84:87]
	v_mfma_f32_4x4x1_16b_f32 v[240:243], v129, v41, v[240:243]
	s_nop 0
	v_mfma_f32_4x4x1_16b_f32 v[84:87], v130, v42, v[84:87]
	v_mfma_f32_4x4x1_16b_f32 v[240:243], v131, v43, v[240:243]
	s_nop 0
	v_mfma_f32_4x4x1_16b_f32 v[84:87], v132, v44, v[84:87]
	v_mfma_f32_4x4x1_16b_f32 v[240:243], v133, v45, v[240:243]
	s_nop 0
	v_mfma_f32_4x4x1_16b_f32 v[84:87], v134, v46, v[84:87]
	v_mfma_f32_4x4x1_16b_f32 v[240:243], v135, v47, v[240:243]
	s_nop 0
	s_waitcnt lgkmcnt(0)
	v_mfma_f32_4x4x1_16b_f32 v[84:87], v88, v72, v[84:87]
	v_mfma_f32_4x4x1_16b_f32 v[240:243], v89, v73, v[240:243]
	s_nop 0
	v_mfma_f32_4x4x1_16b_f32 v[84:87], v90, v74, v[84:87]
	v_mfma_f32_4x4x1_16b_f32 v[240:243], v91, v75, v[240:243]
	s_nop 0
	v_mfma_f32_4x4x1_16b_f32 v[84:87], v92, v76, v[84:87]
	v_mfma_f32_4x4x1_16b_f32 v[240:243], v93, v77, v[240:243]
	s_nop 0
	v_mfma_f32_4x4x1_16b_f32 v[84:87], v94, v78, v[84:87]
	v_mfma_f32_4x4x1_16b_f32 v[240:243], v95, v79, v[240:243]
	s_nop 0
	v_mfma_f32_4x4x1_16b_f32 v[84:87], v96, v80, v[84:87]
	v_mfma_f32_4x4x1_16b_f32 v[240:243], v97, v81, v[240:243]
	s_nop 0
	v_mfma_f32_4x4x1_16b_f32 v[84:87], v98, v82, v[84:87]
	v_mfma_f32_4x4x1_16b_f32 v[240:243], v99, v83, v[240:243]
	s_nop 0
	s_nop 3
	v_pk_add_f32 v[84:85], v[84:85], v[240:241]
	v_pk_add_f32 v[86:87], v[86:87], v[242:243]
	v_mov_b32_e32 v240, 0
	v_mov_b32_e32 v241, 0
	v_mov_b32_e32 v242, 0
	v_mov_b32_e32 v243, 0
	s_nop 3
	v_mov_b32_e32 v235, v84
	s_nop 1
	v_mfma_f32_4x4x1_16b_f32 v[84:87], v100, v235, v[84:87]
	s_nop 1
	s_nop 3
	v_mov_b32_e32 v235, v85
	s_nop 1
	v_mfma_f32_4x4x1_16b_f32 v[84:87], v101, v235, v[84:87]
	s_nop 1
	s_nop 3
	v_mov_b32_e32 v235, v86
	s_nop 1
	v_mfma_f32_4x4x1_16b_f32 v[84:87], v102, v235, v[84:87]
	s_nop 1
	s_nop 4
	v_cvt_pk_bf16_f32 v236, v0, v1
	v_cvt_pk_bf16_f32 v237, v2, v3
	v_cvt_pk_bf16_f32 v238, v4, v5
	v_cvt_pk_bf16_f32 v239, v6, v7
	ds_write_b128 v223, v[236:239] offset:61440
	v_cvt_pk_bf16_f32 v236, v8, v9
	v_cvt_pk_bf16_f32 v237, v10, v11
	v_cvt_pk_bf16_f32 v238, v12, v13
	v_cvt_pk_bf16_f32 v239, v14, v15
	ds_write_b128 v223, v[236:239] offset:61456
	v_cvt_pk_bf16_f32 v236, v16, v17
	v_cvt_pk_bf16_f32 v237, v18, v19
	v_cvt_pk_bf16_f32 v238, v20, v21
	v_cvt_pk_bf16_f32 v239, v22, v23
	ds_write_b128 v223, v[236:239] offset:61472
	v_cvt_pk_bf16_f32 v236, v24, v25
	v_cvt_pk_bf16_f32 v237, v26, v27
	v_cvt_pk_bf16_f32 v238, v28, v29
	v_cvt_pk_bf16_f32 v239, v30, v31
	ds_write_b128 v223, v[236:239] offset:61488
	v_cvt_pk_bf16_f32 v236, v32, v33
	v_cvt_pk_bf16_f32 v237, v34, v35
	v_cvt_pk_bf16_f32 v238, v36, v37
	v_cvt_pk_bf16_f32 v239, v38, v39
	ds_write_b128 v223, v[236:239] offset:61504
	v_cvt_pk_bf16_f32 v236, v40, v41
	v_cvt_pk_bf16_f32 v237, v42, v43
	v_cvt_pk_bf16_f32 v238, v44, v45
	v_cvt_pk_bf16_f32 v239, v46, v47
	ds_write_b128 v223, v[236:239] offset:61520
	v_cvt_pk_bf16_f32 v236, v72, v73
	v_cvt_pk_bf16_f32 v237, v74, v75
	v_cvt_pk_bf16_f32 v238, v76, v77
	v_cvt_pk_bf16_f32 v239, v78, v79
	ds_write_b128 v223, v[236:239] offset:61536
	v_cvt_pk_bf16_f32 v236, v80, v81
	v_cvt_pk_bf16_f32 v237, v82, v83
	v_cvt_pk_bf16_f32 v238, v84, v85
	v_cvt_pk_bf16_f32 v239, v86, v87
	ds_write_b128 v223, v[236:239] offset:61552
